# thin sample-row paths of P3/P4/P6/P7 rewritten by hand: bf16 MFMA 16x16x32 with K split over the 8 waves, all loads in flight, LDS cross-wave reduce (same bf16-in/f32-acc numerics as the GEMM rows)
# speedup vs baseline: 1.0575x; 1.0529x over previous
; __device__ __forceinline__ unsigned f2bf(float f) { unsigned u = __builtin_bit_cast(unsigned, f); return (u + 0x7fffu + ((u >> 16) & 1u)) >> 16; }
; __device__ __forceinline__ float sigmoidf_(float x) { return __builtin_amdgcn_rcpf(1.0f + __builtin_amdgcn_exp2f(-x * LOG2E)); }
; __device__ __forceinline__ float thin_dot(const bf16* __restrict__ a, const bf16* __restrict__ b, int kq) {
;     float s0 = 0.f, s1 = 0.f;
; #pragma unroll 4
;     for (int k = 0; k < kq; k += 8) {
;         const u32x4v x = *(const u32x4v*)(a + k), y = *(const u32x4v*)(b + k);
;         s0 += bflo(x.x) * bflo(y.x) + bflo(x.y) * bflo(y.y) + bflo(x.z) * bflo(y.z) + bflo(x.w) * bflo(y.w);
;         s1 += bfhi(x.x) * bfhi(y.x) + bfhi(x.y) * bfhi(y.y) + bfhi(x.z) * bfhi(y.z) + bfhi(x.w) * bfhi(y.w);
;     }
;     float s = s0 + s1;
;     s += __shfl_xor(s, 1); s += __shfl_xor(s, 2);
;     return s;
; }
; __device__ __forceinline__ void thin_phase(const Params& P, int which, int G) {
;     ...
;     for (int col = blockIdx.x * 4 + c; col < DM; col += G * 4) {
;         if (which == 3) {
;             const bf16* oab = (const bf16*)(ws + WS_QK) + row * KMIX;
;             const float dA = thin_dot(oab + kq * 64, (const bf16*)(ws + WS_WA) + (size_t)col * KMIX + kq * 64, 64);
;             const float dB = thin_dot(oab + 256 + kq * 256, (const bf16*)(ws + WS_WA) + (size_t)col * KMIX + 256 + kq * 256, 256);
;             if (kq == 0) ((bf16*)(ws + WS_XN))[row * DM + col] = (bf16)f2bf(sigmoidf_(bf2f(Z[row * NZ + ZGA + col])) * dA + sigmoidf_(bf2f(Z[row * NZ + ZGB + col])) * dB);
.LBB0_935:
	v_mov_b32_e32 v158, v251
	v_readlane_b32 s98, v252, 4
	v_readlane_b32 s99, v252, 5
	v_readlane_b32 s7, v252, 0
	v_and_b32_e32 v159, 63, v158
	v_lshrrev_b32_e32 v160, 6, v158
	s_load_dwordx2 s[100:101], s[98:99], 0xf0
	s_load_dword s6, s[98:99], 0xf8
	v_and_b32_e32 v161, 15, v159
	v_lshrrev_b32_e32 v162, 4, v159
	v_and_b32_e32 v163, 3, v161
	s_lshl_b32 s7, s7, 2
	s_waitcnt lgkmcnt(0)
	s_lshl_b32 s6, s6, 2
.Lmt3_loop:
	s_cmpk_ge_u32 s7, 0x400
	s_cbranch_scc1 .Lmt3_end
	s_movk_i32 s32, 0x40
	v_mul_u32_u24_e32 v164, s32, v160
	v_lshl_add_u32 v164, v162, 4, v164
	v_mov_b32_e32 v166, 0xa00
	v_mul_u32_u24_e32 v166, v166, v161
	v_add_u32_e32 v166, v166, v164
	v_mov_b32_e32 v167, 0
	s_add_u32 vcc_lo, s100, 0xb2a3500
	s_addc_u32 vcc_hi, s101, 0
	v_lshl_add_u64 v[146:147], vcc, 0, v[166:167]
	s_mov_b32 vcc_lo, 0xa000
	s_mov_b32 vcc_hi, 0
	v_lshl_add_u64 v[148:149], v[146:147], 0, vcc
	v_add_u32_e32 v168, s7, v163
	v_mov_b32_e32 v166, 0xa00
	v_mul_u32_u24_e32 v168, v166, v168
	v_add_u32_e32 v168, v168, v164
	v_mov_b32_e32 v169, 0
	s_add_u32 vcc_lo, s100, 0x1080000
	s_addc_u32 vcc_hi, s101, 0
	v_lshl_add_u64 v[150:151], vcc, 0, v[168:169]
	s_movk_i32 s32, 0x100
	v_mul_u32_u24_e32 v164, s32, v160
	v_lshl_add_u32 v164, v162, 4, v164
	v_mov_b32_e32 v166, 0xa00
	v_mul_u32_u24_e32 v166, v166, v161
	v_add_u32_e32 v166, v166, v164
	v_mov_b32_e32 v167, 0
	s_add_u32 vcc_lo, s100, 0xb2a3700
	s_addc_u32 vcc_hi, s101, 0
	v_lshl_add_u64 v[152:153], vcc, 0, v[166:167]
	s_mov_b32 vcc_lo, 0xa000
	s_mov_b32 vcc_hi, 0
	v_lshl_add_u64 v[154:155], v[152:153], 0, vcc
	v_add_u32_e32 v168, s7, v163
	v_mov_b32_e32 v166, 0xa00
	v_mul_u32_u24_e32 v168, v166, v168
	v_add_u32_e32 v168, v168, v164
	v_mov_b32_e32 v169, 0
	s_add_u32 vcc_lo, s100, 0x1080200
	s_addc_u32 vcc_hi, s101, 0
	v_lshl_add_u64 v[156:157], vcc, 0, v[168:169]
	global_load_dwordx4 v[172:175], v[146:147], off offset:0
	global_load_dwordx4 v[176:179], v[148:149], off offset:0
	global_load_dwordx4 v[180:183], v[150:151], off offset:0
	global_load_dwordx4 v[184:187], v[152:153], off offset:0
	global_load_dwordx4 v[188:191], v[154:155], off offset:0
	global_load_dwordx4 v[192:195], v[156:157], off offset:0
	global_load_dwordx4 v[196:199], v[152:153], off offset:64
	global_load_dwordx4 v[200:203], v[154:155], off offset:64
	global_load_dwordx4 v[204:207], v[156:157], off offset:64
	global_load_dwordx4 v[208:211], v[152:153], off offset:128
	global_load_dwordx4 v[212:215], v[154:155], off offset:128
	global_load_dwordx4 v[216:219], v[156:157], off offset:128
	global_load_dwordx4 v[220:223], v[152:153], off offset:192
	global_load_dwordx4 v[224:227], v[154:155], off offset:192
	global_load_dwordx4 v[228:231], v[156:157], off offset:192
	s_waitcnt vmcnt(12)
	v_mfma_f32_16x16x32_bf16 v[108:111], v[172:175], v[180:183], 0
	v_mfma_f32_16x16x32_bf16 v[112:115], v[176:179], v[180:183], 0
	s_waitcnt vmcnt(9)
	v_mfma_f32_16x16x32_bf16 v[116:119], v[184:187], v[192:195], 0
	v_mfma_f32_16x16x32_bf16 v[120:123], v[188:191], v[192:195], 0
	s_waitcnt vmcnt(6)
	v_mfma_f32_16x16x32_bf16 v[116:119], v[196:199], v[204:207], v[116:119]
	v_mfma_f32_16x16x32_bf16 v[120:123], v[200:203], v[204:207], v[120:123]
	s_waitcnt vmcnt(3)
	v_mfma_f32_16x16x32_bf16 v[116:119], v[208:211], v[216:219], v[116:119]
	v_mfma_f32_16x16x32_bf16 v[120:123], v[212:215], v[216:219], v[120:123]
	s_waitcnt vmcnt(0)
	v_mfma_f32_16x16x32_bf16 v[116:119], v[220:223], v[228:231], v[116:119]
	v_mfma_f32_16x16x32_bf16 v[120:123], v[224:227], v[228:231], v[120:123]
	s_nop 7
	s_nop 3
	v_cmp_gt_u32_e32 vcc, 4, v161
	v_lshlrev_b32_e32 v164, 9, v160
	v_lshl_add_u32 v164, v161, 7, v164
	v_lshl_add_u32 v164, v162, 4, v164
	s_and_saveexec_b64 s[4:5], vcc
	ds_write_b128 v164, v[108:111] offset:0
	ds_write_b128 v164, v[112:115] offset:64
	ds_write_b128 v164, v[116:119] offset:4096
	ds_write_b128 v164, v[120:123] offset:4160
	s_mov_b64 exec, s[4:5]
	s_waitcnt lgkmcnt(0)
	s_barrier
	v_lshrrev_b32_e32 v165, 4, v158
	v_bfe_u32 v166, v158, 2, 2
	v_lshlrev_b32_e32 v167, 2, v165
	v_lshl_add_u32 v167, v166, 7, v167
	ds_read_b32 v172, v167 offset:0
	ds_read_b32 v173, v167 offset:512
	ds_read_b32 v174, v167 offset:1024
	ds_read_b32 v175, v167 offset:1536
	ds_read_b32 v176, v167 offset:2048
	ds_read_b32 v177, v167 offset:2560
	ds_read_b32 v178, v167 offset:3072
	ds_read_b32 v179, v167 offset:3584
	ds_read_b32 v180, v167 offset:4096
	ds_read_b32 v181, v167 offset:4608
	ds_read_b32 v182, v167 offset:5120
	ds_read_b32 v183, v167 offset:5632
	ds_read_b32 v184, v167 offset:6144
	ds_read_b32 v185, v167 offset:6656
	ds_read_b32 v186, v167 offset:7168
	ds_read_b32 v187, v167 offset:7680
	s_waitcnt lgkmcnt(0)
	v_add_f32_e32 v172, v172, v173
	v_add_f32_e32 v174, v174, v175
	v_add_f32_e32 v176, v176, v177
	v_add_f32_e32 v178, v178, v179
	v_add_f32_e32 v172, v172, v174
	v_add_f32_e32 v176, v176, v178
	v_add_f32_e32 v140, v172, v176
	v_add_f32_e32 v180, v180, v181
	v_add_f32_e32 v182, v182, v183
	v_add_f32_e32 v184, v184, v185
	v_add_f32_e32 v186, v186, v187
	v_add_f32_e32 v180, v180, v182
	v_add_f32_e32 v184, v184, v186
	v_add_f32_e32 v141, v180, v184
	v_add_u32_e32 v200, s7, v166
	v_lshl_add_u32 v202, v165, 10, v200
	v_mov_b32_e32 v203, 0
	s_movk_i32 s32, 0x2100
	v_mul_u32_u24_e32 v204, s32, v165
	v_add_u32_e32 v204, v204, v200
	v_mov_b32_e32 v205, 0
	s_add_u32 s98, s100, 0x1f326700
	s_addc_u32 s99, s101, 0
	v_lshl_add_u64 v[204:205], v[204:205], 1, s[98:99]
	global_load_ushort v206, v[204:205], off
	global_load_ushort v218, v[204:205], off offset:2048
	s_add_u32 s98, s100, 0x59c3500
	s_addc_u32 s99, s101, 0
	v_lshl_add_u64 v[208:209], v[202:203], 1, s[98:99]
	s_waitcnt vmcnt(0)
	v_lshlrev_b32_e32 v206, 16, v206
	v_lshlrev_b32_e32 v218, 16, v218
	v_mul_f32_e32 v219, 0xbfb8aa3b, v206
	v_exp_f32_e32 v219, v219
	s_nop 0
	v_add_f32_e32 v219, 1.0, v219
	v_rcp_f32_e32 v219, v219
	s_nop 0
	v_mul_f32_e32 v220, 0xbfb8aa3b, v218
	v_exp_f32_e32 v220, v220
	s_nop 0
	v_add_f32_e32 v220, 1.0, v220
	v_rcp_f32_e32 v220, v220
	s_nop 0
	v_mul_f32_e32 v216, v220, v141
	v_fmac_f32_e32 v216, v219, v140
	v_and_b32_e32 v207, 3, v158
	v_cmp_eq_u32_e32 vcc, 0, v207
	s_and_saveexec_b64 s[4:5], vcc
	v_bfe_u32 v210, v216, 16, 1
	s_movk_i32 s32, 0x7fff
	v_add3_u32 v210, v216, v210, s32
	global_store_short_d16_hi v[208:209], v210, off
	s_mov_b64 exec, s[4:5]
	s_add_u32 s7, s7, s6
	s_barrier
	s_branch .Lmt3_loop
.Lmt3_end:
.LBB0_944:
	s_or_b64 exec, exec, s[4:5]
	s_mov_b32 s12, 1
	s_cmp_lt_i32 s12, 1
	s_cbranch_scc1 .LBB0_908
	s_mov_b32 s13, 0
	s_branch .LBB0_948

; __device__ __forceinline__ unsigned f2bf(float f) { unsigned u = __builtin_bit_cast(unsigned, f); return (u + 0x7fffu + ((u >> 16) & 1u)) >> 16; }
; __device__ __forceinline__ float thin_dot(const bf16* __restrict__ a, const bf16* __restrict__ b, int kq) {
;     float s0 = 0.f, s1 = 0.f;
; #pragma unroll 4
;     for (int k = 0; k < kq; k += 8) {
;         const u32x4v x = *(const u32x4v*)(a + k), y = *(const u32x4v*)(b + k);
;         s0 += bflo(x.x) * bflo(y.x) + bflo(x.y) * bflo(y.y) + bflo(x.z) * bflo(y.z) + bflo(x.w) * bflo(y.w);
;         s1 += bfhi(x.x) * bfhi(y.x) + bfhi(x.y) * bfhi(y.y) + bfhi(x.z) * bfhi(y.z) + bfhi(x.w) * bfhi(y.w);
;     }
;     float s = s0 + s1;
;     s += __shfl_xor(s, 1); s += __shfl_xor(s, 2);
;     return s;
; }
; __device__ __forceinline__ void thin_phase(const Params& P, int which, int G) {
;     ...
;         } else if (which == 4 || which == 6) {
;             float dd, base; float* ss;
;             if (which == 4) { dd = thin_dot((const bf16*)(ws + WS_XN) + row * DM + kq * 256, (const bf16*)(ws + WS_WO) + (size_t)col * DM + kq * 256, 256); base = P.in[1][(size_t)r * DM + col]; ss = (float*)(ws + WS_SS1); }
;             else { dd = thin_dot((const bf16*)(ws + WS_ACT) + row * DFF + kq * 704, (const bf16*)(ws + WS_WD) + (size_t)col * DFF + kq * 704, 704); base = bf2f(HBb[row * DM + col]); ss = (float*)(ws + WS_SS2); }
;             const float hv = base + dd;
;             float sq = hv * hv; sq += __shfl_xor(sq, 4); sq += __shfl_xor(sq, 8);
;             if (kq == 0) { HBb[row * DM + col] = (bf16)f2bf(hv); if (c == 0) atomicAdd(ss + row * 16, sq); }
.LBB0_1038:
	v_mov_b32_e32 v158, v251
	v_readlane_b32 s98, v252, 4
	v_readlane_b32 s99, v252, 5
	v_readlane_b32 s7, v252, 0
	v_and_b32_e32 v159, 63, v158
	v_lshrrev_b32_e32 v160, 6, v158
	s_load_dwordx2 s[100:101], s[98:99], 0xf0
	s_load_dword s6, s[98:99], 0xf8
	s_load_dwordx2 s[8:9], s[98:99], 0x8
	v_and_b32_e32 v161, 15, v159
	v_lshrrev_b32_e32 v162, 4, v159
	v_and_b32_e32 v163, 3, v161
	s_lshl_b32 s7, s7, 2
	s_waitcnt lgkmcnt(0)
	s_lshl_b32 s6, s6, 2
.Lmt4_loop:
	s_cmpk_ge_u32 s7, 0x400
	s_cbranch_scc1 .Lmt4_end
	s_movk_i32 s32, 0x100
	v_mul_u32_u24_e32 v164, s32, v160
	v_lshl_add_u32 v164, v162, 4, v164
	v_mov_b32_e32 v166, 0x800
	v_mul_u32_u24_e32 v166, v166, v161
	v_add_u32_e32 v166, v166, v164
	v_mov_b32_e32 v167, 0
	s_add_u32 vcc_lo, s100, 0x59c3500
	s_addc_u32 vcc_hi, s101, 0
	v_lshl_add_u64 v[146:147], vcc, 0, v[166:167]
	s_mov_b32 vcc_lo, 0x8000
	s_mov_b32 vcc_hi, 0
	v_lshl_add_u64 v[148:149], v[146:147], 0, vcc
	v_add_u32_e32 v168, s7, v163
	v_mov_b32_e32 v166, 0x800
	v_mul_u32_u24_e32 v168, v166, v168
	v_add_u32_e32 v168, v168, v164
	v_mov_b32_e32 v169, 0
	s_add_u32 vcc_lo, s100, 0x1300000
	s_addc_u32 vcc_hi, s101, 0
	v_lshl_add_u64 v[150:151], vcc, 0, v[168:169]
	global_load_dwordx4 v[172:175], v[146:147], off offset:0
	global_load_dwordx4 v[176:179], v[148:149], off offset:0
	global_load_dwordx4 v[180:183], v[150:151], off offset:0
	global_load_dwordx4 v[184:187], v[146:147], off offset:64
	global_load_dwordx4 v[188:191], v[148:149], off offset:64
	global_load_dwordx4 v[192:195], v[150:151], off offset:64
	global_load_dwordx4 v[196:199], v[146:147], off offset:128
	global_load_dwordx4 v[200:203], v[148:149], off offset:128
	global_load_dwordx4 v[204:207], v[150:151], off offset:128
	global_load_dwordx4 v[208:211], v[146:147], off offset:192
	global_load_dwordx4 v[212:215], v[148:149], off offset:192
	global_load_dwordx4 v[216:219], v[150:151], off offset:192
	s_waitcnt vmcnt(9)
	v_mfma_f32_16x16x32_bf16 v[108:111], v[172:175], v[180:183], 0
	v_mfma_f32_16x16x32_bf16 v[112:115], v[176:179], v[180:183], 0
	s_waitcnt vmcnt(6)
	v_mfma_f32_16x16x32_bf16 v[108:111], v[184:187], v[192:195], v[108:111]
	v_mfma_f32_16x16x32_bf16 v[112:115], v[188:191], v[192:195], v[112:115]
	s_waitcnt vmcnt(3)
	v_mfma_f32_16x16x32_bf16 v[108:111], v[196:199], v[204:207], v[108:111]
	v_mfma_f32_16x16x32_bf16 v[112:115], v[200:203], v[204:207], v[112:115]
	s_waitcnt vmcnt(0)
	v_mfma_f32_16x16x32_bf16 v[108:111], v[208:211], v[216:219], v[108:111]
	v_mfma_f32_16x16x32_bf16 v[112:115], v[212:215], v[216:219], v[112:115]
	s_nop 7
	s_nop 3
	v_cmp_gt_u32_e32 vcc, 4, v161
	v_lshlrev_b32_e32 v164, 9, v160
	v_lshl_add_u32 v164, v161, 7, v164
	v_lshl_add_u32 v164, v162, 4, v164
	s_and_saveexec_b64 s[4:5], vcc
	ds_write_b128 v164, v[108:111] offset:0
	ds_write_b128 v164, v[112:115] offset:64
	s_mov_b64 exec, s[4:5]
	s_waitcnt lgkmcnt(0)
	s_barrier
	v_lshrrev_b32_e32 v165, 4, v158
	v_bfe_u32 v166, v158, 2, 2
	v_lshlrev_b32_e32 v167, 2, v165
	v_lshl_add_u32 v167, v166, 7, v167
	ds_read_b32 v172, v167 offset:0
	ds_read_b32 v173, v167 offset:512
	ds_read_b32 v174, v167 offset:1024
	ds_read_b32 v175, v167 offset:1536
	ds_read_b32 v176, v167 offset:2048
	ds_read_b32 v177, v167 offset:2560
	ds_read_b32 v178, v167 offset:3072
	ds_read_b32 v179, v167 offset:3584
	s_waitcnt lgkmcnt(0)
	v_add_f32_e32 v172, v172, v173
	v_add_f32_e32 v174, v174, v175
	v_add_f32_e32 v176, v176, v177
	v_add_f32_e32 v178, v178, v179
	v_add_f32_e32 v172, v172, v174
	v_add_f32_e32 v176, v176, v178
	v_add_f32_e32 v140, v172, v176
	v_add_u32_e32 v200, s7, v166
	v_lshl_add_u32 v202, v165, 10, v200
	v_mov_b32_e32 v203, 0
	v_lshl_add_u64 v[204:205], v[202:203], 2, s[8:9]
	global_load_dword v206, v[204:205], off
	s_add_u32 s98, s100, 0xeaa3500
	s_addc_u32 s99, s101, 0
	v_lshl_add_u64 v[208:209], v[202:203], 1, s[98:99]
	s_waitcnt vmcnt(0)
	v_add_f32_e32 v216, v206, v140
	v_mul_f32_e32 v217, v216, v216
	v_and_b32_e32 v207, 3, v158
	v_cmp_eq_u32_e32 vcc, 0, v207
	s_and_saveexec_b64 s[4:5], vcc
	v_bfe_u32 v210, v216, 16, 1
	s_movk_i32 s32, 0x7fff
	v_add3_u32 v210, v216, v210, s32
	global_store_short_d16_hi v[208:209], v210, off
	s_mov_b64 exec, s[4:5]
	s_nop 1
	v_add_f32_dpp v211, v217, v217 row_shr:4 row_mask:0xf bank_mask:0xf bound_ctrl:1
	s_nop 1
	v_add_f32_dpp v212, v211, v211 row_shr:8 row_mask:0xf bank_mask:0xf bound_ctrl:1
	v_and_b32_e32 v213, 15, v158
	v_cmp_eq_u32_e32 vcc, 12, v213
	v_lshlrev_b32_e32 v214, 6, v165
	v_mov_b32_e32 v215, 0
	s_add_u32 s98, s100, 0x36a3500
	s_addc_u32 s99, s101, 0
	v_lshl_add_u64 v[214:215], s[98:99], 0, v[214:215]
	s_and_saveexec_b64 s[4:5], vcc
	global_atomic_add_f32 v[214:215], v212, off
	s_mov_b64 exec, s[4:5]
	s_add_u32 s7, s7, s6
	s_barrier
	s_branch .Lmt4_loop
.Lmt4_end:
.LBB0_1046:
	s_or_b64 exec, exec, s[4:5]
	s_mov_b32 s20, 1
	s_cmp_lt_i32 s20, 1
	s_cbranch_scc1 .LBB0_1001
	s_mov_b32 s21, 0
	s_branch .LBB0_1050

; __device__ __forceinline__ float thin_dot(const bf16* __restrict__ a, const bf16* __restrict__ b, int kq) {
;     float s0 = 0.f, s1 = 0.f;
; #pragma unroll 4
;     for (int k = 0; k < kq; k += 8) {
;         const u32x4v x = *(const u32x4v*)(a + k), y = *(const u32x4v*)(b + k);
;         s0 += bflo(x.x) * bflo(y.x) + bflo(x.y) * bflo(y.y) + bflo(x.z) * bflo(y.z) + bflo(x.w) * bflo(y.w);
;         s1 += bfhi(x.x) * bfhi(y.x) + bfhi(x.y) * bfhi(y.y) + bfhi(x.z) * bfhi(y.z) + bfhi(x.w) * bfhi(y.w);
;     }
;     float s = s0 + s1;
;     s += __shfl_xor(s, 1); s += __shfl_xor(s, 2);
;     return s;
; }
; __device__ __forceinline__ void thin_phase(const Params& P, int which, int G) {
;     ...
;             float dd, base; float* ss;
;             if (which == 4) { dd = thin_dot((const bf16*)(ws + WS_XN) + row * DM + kq * 256, (const bf16*)(ws + WS_WO) + (size_t)col * DM + kq * 256, 256); base = P.in[1][(size_t)r * DM + col]; ss = (float*)(ws + WS_SS1); }
;             else { dd = thin_dot((const bf16*)(ws + WS_ACT) + row * DFF + kq * 704, (const bf16*)(ws + WS_WD) + (size_t)col * DFF + kq * 704, 704); base = bf2f(HBb[row * DM + col]); ss = (float*)(ws + WS_SS2); }
.LBB0_1225:
	v_mov_b32_e32 v158, v251
	v_readlane_b32 s98, v252, 4
	v_readlane_b32 s99, v252, 5
	v_readlane_b32 s7, v252, 0
	v_and_b32_e32 v159, 63, v158
	v_lshrrev_b32_e32 v160, 6, v158
	s_load_dwordx2 s[100:101], s[98:99], 0xf0
	s_load_dword s6, s[98:99], 0xf8
	v_and_b32_e32 v161, 15, v159
	v_lshrrev_b32_e32 v162, 4, v159
	v_and_b32_e32 v163, 3, v161
	s_lshl_b32 s7, s7, 2
	s_nop 0
	v_writelane_b32 v252, s7, 13
	s_waitcnt lgkmcnt(0)
	s_lshl_b32 s6, s6, 2
.Lmt6_loop:
	s_cmpk_ge_u32 s7, 0x400
	s_cbranch_scc1 .Lmt6_end
	s_movk_i32 s32, 0x2c0
	v_mul_u32_u24_e32 v164, s32, v160
	v_lshl_add_u32 v164, v162, 4, v164
	v_mov_b32_e32 v166, 0x1600
	v_mul_u32_u24_e32 v166, v166, v161
	v_add_u32_e32 v166, v166, v164
	v_mov_b32_e32 v167, 0
	s_add_u32 vcc_lo, s100, 0x18423500
	s_addc_u32 vcc_hi, s101, 0
	v_lshl_add_u64 v[146:147], vcc, 0, v[166:167]
	s_mov_b32 vcc_lo, 0x16000
	s_mov_b32 vcc_hi, 0
	v_lshl_add_u64 v[148:149], v[146:147], 0, vcc
	v_add_u32_e32 v168, s7, v163
	v_mov_b32_e32 v166, 0x1600
	v_mul_u32_u24_e32 v168, v166, v168
	v_add_u32_e32 v168, v168, v164
	v_mov_b32_e32 v169, 0
	s_add_u32 vcc_lo, s100, 0x2000000
	s_addc_u32 vcc_hi, s101, 0
	v_lshl_add_u64 v[150:151], vcc, 0, v[168:169]
	global_load_dwordx4 v[172:175], v[146:147], off offset:0
	global_load_dwordx4 v[176:179], v[148:149], off offset:0
	global_load_dwordx4 v[180:183], v[150:151], off offset:0
	global_load_dwordx4 v[184:187], v[146:147], off offset:64
	global_load_dwordx4 v[188:191], v[148:149], off offset:64
	global_load_dwordx4 v[192:195], v[150:151], off offset:64
	global_load_dwordx4 v[196:199], v[146:147], off offset:128
	global_load_dwordx4 v[200:203], v[148:149], off offset:128
	global_load_dwordx4 v[204:207], v[150:151], off offset:128
	global_load_dwordx4 v[208:211], v[146:147], off offset:192
	global_load_dwordx4 v[212:215], v[148:149], off offset:192
	global_load_dwordx4 v[216:219], v[150:151], off offset:192
	global_load_dwordx4 v[220:223], v[146:147], off offset:256
	global_load_dwordx4 v[224:227], v[148:149], off offset:256
	global_load_dwordx4 v[228:231], v[150:151], off offset:256
	global_load_dwordx4 v[96:99], v[146:147], off offset:320
	global_load_dwordx4 v[100:103], v[148:149], off offset:320
	global_load_dwordx4 v[104:107], v[150:151], off offset:320
	s_waitcnt vmcnt(15)
	v_mfma_f32_16x16x32_bf16 v[108:111], v[172:175], v[180:183], 0
	v_mfma_f32_16x16x32_bf16 v[112:115], v[176:179], v[180:183], 0
	global_load_dwordx4 v[172:175], v[146:147], off offset:384
	global_load_dwordx4 v[176:179], v[148:149], off offset:384
	global_load_dwordx4 v[180:183], v[150:151], off offset:384
	s_waitcnt vmcnt(15)
	v_mfma_f32_16x16x32_bf16 v[108:111], v[184:187], v[192:195], v[108:111]
	v_mfma_f32_16x16x32_bf16 v[112:115], v[188:191], v[192:195], v[112:115]
	global_load_dwordx4 v[184:187], v[146:147], off offset:448
	global_load_dwordx4 v[188:191], v[148:149], off offset:448
	global_load_dwordx4 v[192:195], v[150:151], off offset:448
	s_waitcnt vmcnt(15)
	v_mfma_f32_16x16x32_bf16 v[108:111], v[196:199], v[204:207], v[108:111]
	v_mfma_f32_16x16x32_bf16 v[112:115], v[200:203], v[204:207], v[112:115]
	global_load_dwordx4 v[196:199], v[146:147], off offset:512
	global_load_dwordx4 v[200:203], v[148:149], off offset:512
	global_load_dwordx4 v[204:207], v[150:151], off offset:512
	s_waitcnt vmcnt(15)
	v_mfma_f32_16x16x32_bf16 v[108:111], v[208:211], v[216:219], v[108:111]
	v_mfma_f32_16x16x32_bf16 v[112:115], v[212:215], v[216:219], v[112:115]
	global_load_dwordx4 v[208:211], v[146:147], off offset:576
	global_load_dwordx4 v[212:215], v[148:149], off offset:576
	global_load_dwordx4 v[216:219], v[150:151], off offset:576
	s_waitcnt vmcnt(15)
	v_mfma_f32_16x16x32_bf16 v[108:111], v[220:223], v[228:231], v[108:111]
	v_mfma_f32_16x16x32_bf16 v[112:115], v[224:227], v[228:231], v[112:115]
	global_load_dwordx4 v[220:223], v[146:147], off offset:640
	global_load_dwordx4 v[224:227], v[148:149], off offset:640
	global_load_dwordx4 v[228:231], v[150:151], off offset:640
	s_waitcnt vmcnt(15)
	v_mfma_f32_16x16x32_bf16 v[108:111], v[96:99], v[104:107], v[108:111]
	v_mfma_f32_16x16x32_bf16 v[112:115], v[100:103], v[104:107], v[112:115]
	s_waitcnt vmcnt(12)
	v_mfma_f32_16x16x32_bf16 v[108:111], v[172:175], v[180:183], v[108:111]
	v_mfma_f32_16x16x32_bf16 v[112:115], v[176:179], v[180:183], v[112:115]
	s_waitcnt vmcnt(9)
	v_mfma_f32_16x16x32_bf16 v[108:111], v[184:187], v[192:195], v[108:111]
	v_mfma_f32_16x16x32_bf16 v[112:115], v[188:191], v[192:195], v[112:115]
	s_waitcnt vmcnt(6)
	v_mfma_f32_16x16x32_bf16 v[108:111], v[196:199], v[204:207], v[108:111]
	v_mfma_f32_16x16x32_bf16 v[112:115], v[200:203], v[204:207], v[112:115]
	s_waitcnt vmcnt(3)
	v_mfma_f32_16x16x32_bf16 v[108:111], v[208:211], v[216:219], v[108:111]
	v_mfma_f32_16x16x32_bf16 v[112:115], v[212:215], v[216:219], v[112:115]
	s_waitcnt vmcnt(0)
	v_mfma_f32_16x16x32_bf16 v[108:111], v[220:223], v[228:231], v[108:111]
	v_mfma_f32_16x16x32_bf16 v[112:115], v[224:227], v[228:231], v[112:115]
	s_nop 7
	s_nop 3
	v_cmp_gt_u32_e32 vcc, 4, v161
	v_lshlrev_b32_e32 v164, 9, v160
	v_lshl_add_u32 v164, v161, 7, v164
	v_lshl_add_u32 v164, v162, 4, v164
	s_and_saveexec_b64 s[4:5], vcc
	ds_write_b128 v164, v[108:111] offset:0
	ds_write_b128 v164, v[112:115] offset:64
	s_mov_b64 exec, s[4:5]
	s_waitcnt lgkmcnt(0)
	s_barrier
; __device__ __forceinline__ unsigned f2bf(float f) { unsigned u = __builtin_bit_cast(unsigned, f); return (u + 0x7fffu + ((u >> 16) & 1u)) >> 16; }
; __device__ __forceinline__ void thin_phase(const Params& P, int which, int G) {
;     ...
;             else { dd = thin_dot((const bf16*)(ws + WS_ACT) + row * DFF + kq * 704, (const bf16*)(ws + WS_WD) + (size_t)col * DFF + kq * 704, 704); base = bf2f(HBb[row * DM + col]); ss = (float*)(ws + WS_SS2); }
;             const float hv = base + dd;
;             float sq = hv * hv; sq += __shfl_xor(sq, 4); sq += __shfl_xor(sq, 8);
;             if (kq == 0) { HBb[row * DM + col] = (bf16)f2bf(hv); if (c == 0) atomicAdd(ss + row * 16, sq); }
	v_lshrrev_b32_e32 v165, 4, v158
	v_bfe_u32 v166, v158, 2, 2
	v_lshlrev_b32_e32 v167, 2, v165
	v_lshl_add_u32 v167, v166, 7, v167
	ds_read_b32 v172, v167 offset:0
	ds_read_b32 v173, v167 offset:512
	ds_read_b32 v174, v167 offset:1024
	ds_read_b32 v175, v167 offset:1536
	ds_read_b32 v176, v167 offset:2048
	ds_read_b32 v177, v167 offset:2560
	ds_read_b32 v178, v167 offset:3072
	ds_read_b32 v179, v167 offset:3584
	s_waitcnt lgkmcnt(0)
	v_add_f32_e32 v172, v172, v173
	v_add_f32_e32 v174, v174, v175
	v_add_f32_e32 v176, v176, v177
	v_add_f32_e32 v178, v178, v179
	v_add_f32_e32 v172, v172, v174
	v_add_f32_e32 v176, v176, v178
	v_add_f32_e32 v140, v172, v176
	v_add_u32_e32 v200, s7, v166
	v_lshl_add_u32 v202, v165, 10, v200
	v_mov_b32_e32 v203, 0
	s_add_u32 s98, s100, 0xeaa3500
	s_addc_u32 s99, s101, 0
	v_lshl_add_u64 v[208:209], v[202:203], 1, s[98:99]
	global_load_ushort v206, v[208:209], off
	s_waitcnt vmcnt(0)
	v_lshlrev_b32_e32 v206, 16, v206
	v_add_f32_e32 v216, v206, v140
	v_mul_f32_e32 v217, v216, v216
	v_and_b32_e32 v207, 3, v158
	v_cmp_eq_u32_e32 vcc, 0, v207
	s_and_saveexec_b64 s[4:5], vcc
	v_bfe_u32 v210, v216, 16, 1
	s_movk_i32 s32, 0x7fff
	v_add3_u32 v210, v216, v210, s32
	global_store_short_d16_hi v[208:209], v210, off
	s_mov_b64 exec, s[4:5]
	s_nop 1
	v_add_f32_dpp v211, v217, v217 row_shr:4 row_mask:0xf bank_mask:0xf bound_ctrl:1
	s_nop 1
	v_add_f32_dpp v212, v211, v211 row_shr:8 row_mask:0xf bank_mask:0xf bound_ctrl:1
	v_and_b32_e32 v213, 15, v158
	v_cmp_eq_u32_e32 vcc, 12, v213
	v_lshlrev_b32_e32 v214, 6, v165
	v_mov_b32_e32 v215, 0
	s_add_u32 s98, s100, 0x37a7500
	s_addc_u32 s99, s101, 0
	v_lshl_add_u64 v[214:215], s[98:99], 0, v[214:215]
	s_and_saveexec_b64 s[4:5], vcc
	global_atomic_add_f32 v[214:215], v212, off
	s_mov_b64 exec, s[4:5]
	s_add_u32 s7, s7, s6
	s_barrier
	s_branch .Lmt6_loop
.Lmt6_end:
.LBB0_1233:
	s_or_b64 exec, exec, s[10:11]
	s_mov_b32 s33, 1
	s_mul_i32 s0, s31, s30
	v_readlane_b32 s1, v252, 1
	s_cmp_lt_i32 s33, 1
	s_mul_i32 s0, s0, s1
	s_cbranch_scc1 .LBB0_1288
	v_readlane_b32 s4, v252, 4
	v_readlane_b32 s5, v252, 5
	s_load_dwordx4 s[84:87], s[4:5], 0xf0
	v_readlane_b32 s4, v252, 10
	s_mov_b32 s1, 0
	v_mov_b32_e32 v2, 0
	v_mov_b32_e32 v3, 1
	s_waitcnt lgkmcnt(0)
	s_add_u32 s42, s84, 0x38bf700
	s_addc_u32 s43, s85, 0
	s_add_u32 s44, s84, 0x38bf900
	s_addc_u32 s45, s85, 0
	s_add_u32 s46, s84, 0x38bfa00
	s_addc_u32 s47, s85, 0
	s_add_u32 s48, s84, 0x38bfb00
	s_addc_u32 s49, s85, 0
	s_add_u32 s50, s84, 0x38bfc00
	s_addc_u32 s51, s85, 0
	s_add_u32 s52, s84, 0x38bfd00
	s_addc_u32 s53, s85, 0
	s_add_u32 s54, s84, 0x38bfe00
	s_addc_u32 s55, s85, 0
	s_add_u32 s56, s84, 0x38bff00
	s_addc_u32 s57, s85, 0
	s_add_u32 s58, s84, 0x38c0000
	s_addc_u32 s59, s85, 0
	s_add_u32 s60, s84, 0x38c0100
	s_addc_u32 s61, s85, 0
	s_add_u32 s62, s84, 0x38c0200
	s_addc_u32 s63, s85, 0
	s_add_u32 s64, s84, 0x38c0300
	s_addc_u32 s65, s85, 0
	s_add_u32 s66, s84, 0x38c0400
	s_addc_u32 s67, s85, 0
	s_add_u32 s68, s84, 0x38c0500
	s_addc_u32 s69, s85, 0
	s_add_u32 s70, s84, 0x38c0600
	s_addc_u32 s71, s85, 0
	s_add_u32 s72, s84, 0x38c0700
	s_addc_u32 s73, s85, 0
	s_add_u32 s74, s84, 0x38c0800
	s_addc_u32 s75, s85, 0
	s_cmp_eq_u32 s4, 15
	s_cselect_b64 s[6:7], -1, 0
	v_writelane_b32 v252, s6, 60
	s_cmp_eq_u32 s4, 14
	s_mov_b64 s[8:9], s[94:95]
	v_writelane_b32 v252, s7, 61
	s_cselect_b64 s[6:7], -1, 0
	s_cmp_eq_u32 s4, 13
	s_cselect_b64 s[10:11], -1, 0
	s_cmp_eq_u32 s4, 12
	s_cselect_b64 s[40:41], -1, 0
	s_cmp_eq_u32 s4, 11
	s_cselect_b64 s[14:15], -1, 0
	s_cmp_eq_u32 s4, 10
	s_cselect_b64 s[16:17], -1, 0
	s_cmp_eq_u32 s4, 9
	s_cselect_b64 s[18:19], -1, 0
	s_cmp_eq_u32 s4, 8
	s_cselect_b64 s[12:13], -1, 0
	s_cmp_eq_u32 s4, 7
	s_cselect_b64 s[22:23], -1, 0
	s_cmp_eq_u32 s4, 6
	s_cselect_b64 s[24:25], -1, 0
	s_cmp_eq_u32 s4, 5
	s_cselect_b64 s[26:27], -1, 0
	s_cmp_eq_u32 s4, 4
	s_cselect_b64 s[28:29], -1, 0
	s_cmp_eq_u32 s4, 3
	s_cselect_b64 s[30:31], -1, 0
	s_cmp_eq_u32 s4, 2
	v_writelane_b32 v252, s6, 14
	s_cselect_b64 s[20:21], -1, 0
	s_cmp_eq_u32 s4, 1
	v_writelane_b32 v252, s7, 15
	s_cselect_b64 s[36:37], -1, 0
	s_cmp_eq_u32 s4, 0
	s_cselect_b64 s[38:39], -1, 0
	s_lshl_b32 s4, s4, 8
	v_readlane_b32 s6, v252, 2
	v_readlane_b32 s7, v252, 3
	s_add_u32 s4, s6, s4
	s_addc_u32 s5, s7, 0
	s_add_u32 s76, s4, 0x1400
	s_addc_u32 s77, s5, 0
	s_add_u32 s78, s4, 0x2400
	s_addc_u32 s79, s5, 0
	s_add_u32 s80, s84, 0x38c2900
	s_addc_u32 s81, s85, 0
	s_add_u32 s82, s84, 0x38c2a00
	s_addc_u32 s83, s85, 0
	s_add_i32 s4, 0, 0x22fc0
	s_add_i32 s5, 0, 0x22fc4
	s_branch .LBB0_1237

; __device__ __forceinline__ float thin_dot(const bf16* __restrict__ a, const bf16* __restrict__ b, int kq) {
;     float s0 = 0.f, s1 = 0.f;
; #pragma unroll 4
;     for (int k = 0; k < kq; k += 8) {
;         const u32x4v x = *(const u32x4v*)(a + k), y = *(const u32x4v*)(b + k);
;         s0 += bflo(x.x) * bflo(y.x) + bflo(x.y) * bflo(y.y) + bflo(x.z) * bflo(y.z) + bflo(x.w) * bflo(y.w);
;         s1 += bfhi(x.x) * bfhi(y.x) + bfhi(x.y) * bfhi(y.y) + bfhi(x.z) * bfhi(y.z) + bfhi(x.w) * bfhi(y.w);
;     }
;     float s = s0 + s1;
;     s += __shfl_xor(s, 1); s += __shfl_xor(s, 2);
;     return s;
; }
; __device__ __forceinline__ void thin_phase(const Params& P, int which, int G) {
;     ...
;         } else {
;             const float dp = thin_dot((const bf16*)(ws + WS_PB) + row * 256 + kq * 64, (const bf16*)(ws + WS_WPP) + (size_t)col * 256 + kq * 64, 64);
;             const float dg = thin_dot(HBb + row * DM + kq * 256, (const bf16*)(ws + WS_WPG) + (size_t)col * DM + kq * 256, 256);
.Lmt7_loop:
	s_cmpk_ge_u32 s7, 0x400
	s_cbranch_scc1 .Lmt7_end
	s_movk_i32 s32, 0x40
	v_mul_u32_u24_e32 v164, s32, v160
	v_lshl_add_u32 v164, v162, 4, v164
	v_mov_b32_e32 v166, 0x200
	v_mul_u32_u24_e32 v166, v166, v161
	v_add_u32_e32 v166, v166, v164
	v_mov_b32_e32 v167, 0
	s_add_u32 vcc_lo, s100, 0x30c0500
	s_addc_u32 vcc_hi, s101, 0
	v_lshl_add_u64 v[146:147], vcc, 0, v[166:167]
	s_mov_b32 vcc_lo, 0x2000
	s_mov_b32 vcc_hi, 0
	v_lshl_add_u64 v[148:149], v[146:147], 0, vcc
	v_add_u32_e32 v168, s7, v163
	v_mov_b32_e32 v166, 0x200
	v_mul_u32_u24_e32 v168, v166, v168
	v_add_u32_e32 v168, v168, v164
	v_mov_b32_e32 v169, 0
	s_add_u32 vcc_lo, s100, 0x2780000
	s_addc_u32 vcc_hi, s101, 0
	v_lshl_add_u64 v[150:151], vcc, 0, v[168:169]
	s_movk_i32 s32, 0x100
	v_mul_u32_u24_e32 v164, s32, v160
	v_lshl_add_u32 v164, v162, 4, v164
	v_mov_b32_e32 v166, 0x800
	v_mul_u32_u24_e32 v166, v166, v161
	v_add_u32_e32 v166, v166, v164
	v_mov_b32_e32 v167, 0
	s_add_u32 vcc_lo, s100, 0xeaa3500
	s_addc_u32 vcc_hi, s101, 0
	v_lshl_add_u64 v[152:153], vcc, 0, v[166:167]
	s_mov_b32 vcc_lo, 0x8000
	s_mov_b32 vcc_hi, 0
	v_lshl_add_u64 v[154:155], v[152:153], 0, vcc
	v_add_u32_e32 v168, s7, v163
	v_mov_b32_e32 v166, 0x800
	v_mul_u32_u24_e32 v168, v166, v168
	v_add_u32_e32 v168, v168, v164
	v_mov_b32_e32 v169, 0
	s_add_u32 vcc_lo, s100, 0x2580000
	s_addc_u32 vcc_hi, s101, 0
	v_lshl_add_u64 v[156:157], vcc, 0, v[168:169]
	global_load_dwordx4 v[172:175], v[146:147], off offset:0
	global_load_dwordx4 v[176:179], v[148:149], off offset:0
	global_load_dwordx4 v[180:183], v[150:151], off offset:0
	global_load_dwordx4 v[184:187], v[152:153], off offset:0
	global_load_dwordx4 v[188:191], v[154:155], off offset:0
	global_load_dwordx4 v[192:195], v[156:157], off offset:0
	global_load_dwordx4 v[196:199], v[152:153], off offset:64
	global_load_dwordx4 v[200:203], v[154:155], off offset:64
	global_load_dwordx4 v[204:207], v[156:157], off offset:64
	global_load_dwordx4 v[208:211], v[152:153], off offset:128
	global_load_dwordx4 v[212:215], v[154:155], off offset:128
	global_load_dwordx4 v[216:219], v[156:157], off offset:128
	global_load_dwordx4 v[220:223], v[152:153], off offset:192
	global_load_dwordx4 v[224:227], v[154:155], off offset:192
	global_load_dwordx4 v[228:231], v[156:157], off offset:192
	s_waitcnt vmcnt(12)
	v_mfma_f32_16x16x32_bf16 v[108:111], v[172:175], v[180:183], 0
	v_mfma_f32_16x16x32_bf16 v[112:115], v[176:179], v[180:183], 0
	s_waitcnt vmcnt(9)
	v_mfma_f32_16x16x32_bf16 v[116:119], v[184:187], v[192:195], 0
	v_mfma_f32_16x16x32_bf16 v[120:123], v[188:191], v[192:195], 0
	s_waitcnt vmcnt(6)
	v_mfma_f32_16x16x32_bf16 v[116:119], v[196:199], v[204:207], v[116:119]
	v_mfma_f32_16x16x32_bf16 v[120:123], v[200:203], v[204:207], v[120:123]
	s_waitcnt vmcnt(3)
	v_mfma_f32_16x16x32_bf16 v[116:119], v[208:211], v[216:219], v[116:119]
	v_mfma_f32_16x16x32_bf16 v[120:123], v[212:215], v[216:219], v[120:123]
	s_waitcnt vmcnt(0)
	v_mfma_f32_16x16x32_bf16 v[116:119], v[220:223], v[228:231], v[116:119]
	v_mfma_f32_16x16x32_bf16 v[120:123], v[224:227], v[228:231], v[120:123]
	s_nop 7
	s_nop 3
	v_cmp_gt_u32_e32 vcc, 4, v161
	v_lshlrev_b32_e32 v164, 9, v160
	v_lshl_add_u32 v164, v161, 7, v164
	v_lshl_add_u32 v164, v162, 4, v164
	s_and_saveexec_b64 s[4:5], vcc
	ds_write_b128 v164, v[108:111] offset:0
	ds_write_b128 v164, v[112:115] offset:64
	ds_write_b128 v164, v[116:119] offset:4096
	ds_write_b128 v164, v[120:123] offset:4160
	s_mov_b64 exec, s[4:5]
	s_waitcnt lgkmcnt(0)
	s_barrier
; __device__ __forceinline__ unsigned f2bf(float f) { unsigned u = __builtin_bit_cast(unsigned, f); return (u + 0x7fffu + ((u >> 16) & 1u)) >> 16; }
; __device__ __forceinline__ float sigmoidf_(float x) { return __builtin_amdgcn_rcpf(1.0f + __builtin_amdgcn_exp2f(-x * LOG2E)); }
; __device__ __forceinline__ float row_rs(const float* ss, int row) {
;     const f32x4* sp = (const f32x4*)(ss + (size_t)row * 16);
;     const f32x4 a = sp[0], b = sp[1], c = sp[2], d = sp[3];
;     const float tot = ((a[0] + a[1]) + (a[2] + a[3])) + ((b[0] + b[1]) + (b[2] + b[3])) + ((c[0] + c[1]) + (c[2] + c[3])) + ((d[0] + d[1]) + (d[2] + d[3]));
;     return __builtin_amdgcn_rsqf(tot * (1.0f / 1024.0f) + EPSN);
; }
; __device__ __forceinline__ void thin_phase(const Params& P, int which, int G) {
;     ...
;             const float dg = thin_dot(HBb + row * DM + kq * 256, (const bf16*)(ws + WS_WPG) + (size_t)col * DM + kq * 256, 256);
;             const float rs = pg8::row_rs((const float*)(ws + WS_SS2), (int)row);
;             const float hv = bf2f(HBb[row * DM + col]) + sigmoidf_(rs * dg) * dp;
;             float sq = hv * hv; sq += __shfl_xor(sq, 4); sq += __shfl_xor(sq, 8);
;             if (kq == 0) { ((bf16*)(ws + WS_XN))[row * DM + col] = (bf16)f2bf(hv); if (c == 0) atomicAdd((float*)(ws + WS_SS3) + row * 16, sq); }
	v_lshrrev_b32_e32 v165, 4, v158
	v_bfe_u32 v166, v158, 2, 2
	v_lshlrev_b32_e32 v167, 2, v165
	v_lshl_add_u32 v167, v166, 7, v167
	ds_read_b32 v172, v167 offset:0
	ds_read_b32 v173, v167 offset:512
	ds_read_b32 v174, v167 offset:1024
	ds_read_b32 v175, v167 offset:1536
	ds_read_b32 v176, v167 offset:2048
	ds_read_b32 v177, v167 offset:2560
	ds_read_b32 v178, v167 offset:3072
	ds_read_b32 v179, v167 offset:3584
	ds_read_b32 v180, v167 offset:4096
	ds_read_b32 v181, v167 offset:4608
	ds_read_b32 v182, v167 offset:5120
	ds_read_b32 v183, v167 offset:5632
	ds_read_b32 v184, v167 offset:6144
	ds_read_b32 v185, v167 offset:6656
	ds_read_b32 v186, v167 offset:7168
	ds_read_b32 v187, v167 offset:7680
	s_waitcnt lgkmcnt(0)
	v_add_f32_e32 v172, v172, v173
	v_add_f32_e32 v174, v174, v175
	v_add_f32_e32 v176, v176, v177
	v_add_f32_e32 v178, v178, v179
	v_add_f32_e32 v172, v172, v174
	v_add_f32_e32 v176, v176, v178
	v_add_f32_e32 v140, v172, v176
	v_add_f32_e32 v180, v180, v181
	v_add_f32_e32 v182, v182, v183
	v_add_f32_e32 v184, v184, v185
	v_add_f32_e32 v186, v186, v187
	v_add_f32_e32 v180, v180, v182
	v_add_f32_e32 v184, v184, v186
	v_add_f32_e32 v141, v180, v184
	v_add_u32_e32 v200, s7, v166
	v_lshl_add_u32 v202, v165, 10, v200
	v_mov_b32_e32 v203, 0
	v_lshlrev_b32_e32 v204, 6, v165
	v_mov_b32_e32 v205, 0
	s_add_u32 s98, s100, 0x37a7500
	s_addc_u32 s99, s101, 0
	v_lshl_add_u64 v[204:205], s[98:99], 0, v[204:205]
	global_load_dwordx4 v[180:183], v[204:205], off
	global_load_dwordx4 v[184:187], v[204:205], off offset:16
	global_load_dwordx4 v[188:191], v[204:205], off offset:32
	global_load_dwordx4 v[192:195], v[204:205], off offset:48
	s_add_u32 s98, s100, 0xeaa3500
	s_addc_u32 s99, s101, 0
	v_lshl_add_u64 v[208:209], v[202:203], 1, s[98:99]
	global_load_ushort v206, v[208:209], off
	s_add_u32 s98, s100, 0x59c3500
	s_addc_u32 s99, s101, 0
	v_lshl_add_u64 v[196:197], v[202:203], 1, s[98:99]
	s_waitcnt vmcnt(0)
	v_add_f32_e32 v180, v180, v181
	v_add_f32_e32 v182, v182, v183
	v_add_f32_e32 v180, v180, v182
	v_add_f32_e32 v184, v184, v185
	v_add_f32_e32 v186, v186, v187
	v_add_f32_e32 v184, v184, v186
	v_add_f32_e32 v188, v188, v189
	v_add_f32_e32 v190, v190, v191
	v_add_f32_e32 v188, v188, v190
	v_add_f32_e32 v192, v192, v193
	v_add_f32_e32 v194, v194, v195
	v_add_f32_e32 v192, v192, v194
	v_add_f32_e32 v180, v180, v184
	v_add_f32_e32 v188, v188, v192
	v_add_f32_e32 v180, v180, v188
	v_mov_b32_e32 v198, 0x358637bd
	v_fmamk_f32 v180, v180, 0x3a800000, v198
	v_rsq_f32_e32 v180, v180
	s_nop 0
	v_mul_f32_e32 v181, v180, v141
	v_mul_f32_e32 v182, 0xbfb8aa3b, v181
	v_exp_f32_e32 v182, v182
	s_nop 0
	v_add_f32_e32 v182, 1.0, v182
	v_rcp_f32_e32 v182, v182
	s_nop 0
	v_lshlrev_b32_e32 v206, 16, v206
	v_fma_f32 v216, v182, v140, v206
	v_mul_f32_e32 v217, v216, v216
	v_and_b32_e32 v207, 3, v158
	v_cmp_eq_u32_e32 vcc, 0, v207
	s_and_saveexec_b64 s[4:5], vcc
	v_bfe_u32 v210, v216, 16, 1
	s_movk_i32 s32, 0x7fff
	v_add3_u32 v210, v216, v210, s32
	global_store_short_d16_hi v[196:197], v210, off
	s_mov_b64 exec, s[4:5]
	s_nop 1
	v_add_f32_dpp v211, v217, v217 row_shr:4 row_mask:0xf bank_mask:0xf bound_ctrl:1
	s_nop 1
	v_add_f32_dpp v212, v211, v211 row_shr:8 row_mask:0xf bank_mask:0xf bound_ctrl:1
	v_and_b32_e32 v213, 15, v158
	v_cmp_eq_u32_e32 vcc, 12, v213
	v_lshlrev_b32_e32 v214, 6, v165
	v_mov_b32_e32 v215, 0
	s_add_u32 s98, s100, 0x38ab500
	s_addc_u32 s99, s101, 0
	v_lshl_add_u64 v[214:215], s[98:99], 0, v[214:215]
	s_and_saveexec_b64 s[4:5], vcc
	global_atomic_add_f32 v[214:215], v212, off
	s_mov_b64 exec, s[4:5]
	s_add_u32 s7, s7, s6
	s_barrier
	s_branch .Lmt7_loop
.Lmt7_end:
.LBB0_1368:
	s_or_b64 exec, exec, s[2:3]
	s_mov_b32 s1, 1
	s_cmp_lt_i32 s1, 1
	s_mov_b32 s33, 1
	s_cbranch_scc1 .LBB0_1423
	v_readlane_b32 s2, v252, 4
	v_readlane_b32 s3, v252, 5
	s_load_dwordx4 s[76:79], s[2:3], 0xf0
	v_readlane_b32 s70, v252, 10
	v_readlane_b32 s72, v252, 2
	v_readlane_b32 s73, v252, 3
	s_mov_b32 s94, 0
	s_waitcnt lgkmcnt(0)
	s_add_u32 s2, s76, 0x38bf700
	s_addc_u32 s3, s77, 0
	s_add_u32 s34, s76, 0x38bf900
	s_addc_u32 s35, s77, 0
	s_add_u32 s40, s76, 0x38bfa00
	s_addc_u32 s41, s77, 0
	s_add_u32 s42, s76, 0x38bfb00
	s_addc_u32 s43, s77, 0
	s_add_u32 s44, s76, 0x38bfc00
	s_addc_u32 s45, s77, 0
	s_add_u32 s46, s76, 0x38bfd00
	s_addc_u32 s47, s77, 0
	s_add_u32 s48, s76, 0x38bfe00
	s_addc_u32 s49, s77, 0
	s_add_u32 s50, s76, 0x38bff00
	s_addc_u32 s51, s77, 0
	s_add_u32 s52, s76, 0x38c0000
	s_addc_u32 s53, s77, 0
	s_add_u32 s54, s76, 0x38c0100
	s_addc_u32 s55, s77, 0
	s_add_u32 s56, s76, 0x38c0200
	s_addc_u32 s57, s77, 0
	s_add_u32 s58, s76, 0x38c0300
	s_addc_u32 s59, s77, 0
	s_add_u32 s60, s76, 0x38c0400
	s_addc_u32 s61, s77, 0
	s_add_u32 s62, s76, 0x38c0500
	s_addc_u32 s63, s77, 0
	s_add_u32 s64, s76, 0x38c0600
	s_addc_u32 s65, s77, 0
	s_add_u32 s66, s76, 0x38c0700
	s_addc_u32 s67, s77, 0
	s_add_u32 s68, s76, 0x38c0800
	s_addc_u32 s69, s77, 0
	s_cmp_eq_u32 s70, 15
	s_cselect_b64 s[4:5], -1, 0
	s_cmp_eq_u32 s70, 14
	s_cselect_b64 s[6:7], -1, 0
	s_cmp_eq_u32 s70, 13
	s_cselect_b64 s[8:9], -1, 0
	s_cmp_eq_u32 s70, 12
	s_cselect_b64 s[10:11], -1, 0
	s_cmp_eq_u32 s70, 11
	s_cselect_b64 s[38:39], -1, 0
	s_cmp_eq_u32 s70, 10
	s_cselect_b64 s[14:15], -1, 0
	s_cmp_eq_u32 s70, 9
	s_cselect_b64 s[16:17], -1, 0
	s_cmp_eq_u32 s70, 8
	s_cselect_b64 s[18:19], -1, 0
	s_cmp_eq_u32 s70, 7
	s_cselect_b64 s[12:13], -1, 0
	s_cmp_eq_u32 s70, 6
	s_cselect_b64 s[22:23], -1, 0
	s_cmp_eq_u32 s70, 5
	s_cselect_b64 s[24:25], -1, 0
	s_cmp_eq_u32 s70, 4
	s_cselect_b64 s[26:27], -1, 0
	s_cmp_eq_u32 s70, 3
	s_cselect_b64 s[28:29], -1, 0
	s_cmp_eq_u32 s70, 2
	s_cselect_b64 s[30:31], -1, 0
	s_cmp_eq_u32 s70, 1
	s_cselect_b64 s[20:21], -1, 0
	s_cmp_eq_u32 s70, 0
	s_cselect_b64 s[36:37], -1, 0
	s_lshl_b32 s70, s70, 8
	s_add_u32 s72, s72, s70
	s_addc_u32 s73, s73, 0
	s_add_u32 s70, s72, 0x1400
	s_addc_u32 s71, s73, 0
	s_add_u32 s72, s72, 0x2400
	s_addc_u32 s73, s73, 0
	s_add_u32 s74, s76, 0x38c2900
	s_addc_u32 s75, s77, 0
	s_add_u32 s76, s76, 0x38c2a00
	s_addc_u32 s77, s77, 0
	s_add_i32 s95, 0, 0x22fc0
	s_add_i32 s96, 0, 0x22fc4
	v_mov_b32_e32 v2, 0
	v_mov_b32_e32 v3, 1
	s_branch .LBB0_1372

; #define LAS __attribute__((address_space(3)))
; __global__ void __launch_bounds__(512) hybrid_step_fwd(Params P) {
;     extern __shared__ __attribute__((aligned(16))) unsigned char lds_raw[];
;     LAS unsigned char* lds = (LAS unsigned char*)lds_raw;
	.amdhsa_kernel _Z15hybrid_step_fwd6Params
		.amdhsa_group_segment_fixed_size 0
		.amdhsa_private_segment_fixed_size 0
		.amdhsa_kernarg_size 504
		.amdhsa_user_sgpr_count 2
		.amdhsa_user_sgpr_dispatch_ptr 0
		.amdhsa_user_sgpr_queue_ptr 0
		.amdhsa_user_sgpr_kernarg_segment_ptr 1
		.amdhsa_user_sgpr_dispatch_id 0
		.amdhsa_user_sgpr_kernarg_preload_length 0
		.amdhsa_user_sgpr_kernarg_preload_offset 0
		.amdhsa_user_sgpr_private_segment_size 0
		.amdhsa_uses_dynamic_stack 0
		.amdhsa_enable_private_segment 0
		.amdhsa_system_sgpr_workgroup_id_x 1
		.amdhsa_system_sgpr_workgroup_id_y 0
		.amdhsa_system_sgpr_workgroup_id_z 0
		.amdhsa_system_sgpr_workgroup_info 0
		.amdhsa_system_vgpr_workitem_id 2
		.amdhsa_next_free_vgpr 256
		.amdhsa_next_free_sgpr 102
		.amdhsa_accum_offset 256
		.amdhsa_reserve_vcc 1
		.amdhsa_float_round_mode_32 0
		.amdhsa_float_round_mode_16_64 0
		.amdhsa_float_denorm_mode_32 3
		.amdhsa_float_denorm_mode_16_64 3
		.amdhsa_dx10_clamp 1
		.amdhsa_ieee_mode 1
		.amdhsa_fp16_overflow 0
		.amdhsa_tg_split 0
		.amdhsa_exception_fp_ieee_invalid_op 0
		.amdhsa_exception_fp_denorm_src 0
		.amdhsa_exception_fp_ieee_div_zero 0
		.amdhsa_exception_fp_ieee_overflow 0
		.amdhsa_exception_fp_ieee_underflow 0
		.amdhsa_exception_fp_ieee_inexact 0
		.amdhsa_exception_int_div_zero 0
	.end_amdhsa_kernel

amdhsa.kernels:
  - .agpr_count:     0
    .args:
      - .offset:         0
        .size:           248
        .value_kind:     by_value
      - .offset:         248
        .size:           4
        .value_kind:     hidden_block_count_x
      - .offset:         252
        .size:           4
        .value_kind:     hidden_block_count_y
      - .offset:         256
        .size:           4
        .value_kind:     hidden_block_count_z
      - .offset:         260
        .size:           2
        .value_kind:     hidden_group_size_x
      - .offset:         262
        .size:           2
        .value_kind:     hidden_group_size_y
      - .offset:         264
        .size:           2
        .value_kind:     hidden_group_size_z
      - .offset:         266
        .size:           2
        .value_kind:     hidden_remainder_x
      - .offset:         268
        .size:           2
        .value_kind:     hidden_remainder_y
      - .offset:         270
        .size:           2
        .value_kind:     hidden_remainder_z
      - .offset:         288
        .size:           8
        .value_kind:     hidden_global_offset_x
      - .offset:         296
        .size:           8
        .value_kind:     hidden_global_offset_y
      - .offset:         304
        .size:           8
        .value_kind:     hidden_global_offset_z
      - .offset:         312
        .size:           2
        .value_kind:     hidden_grid_dims
      - .offset:         336
        .size:           8
        .value_kind:     hidden_multigrid_sync_arg
      - .offset:         368
        .size:           4
        .value_kind:     hidden_dynamic_lds_size
    .group_segment_fixed_size: 0
    .kernarg_segment_align: 8
    .kernarg_segment_size: 504
    .language:       OpenCL C
    .language_version:
      - 2
      - 0
    .max_flat_workgroup_size: 512
    .name:           _Z15hybrid_step_fwd6Params
    .private_segment_fixed_size: 0
    .sgpr_count:     108
    .sgpr_spill_count: 505
    .symbol:         _Z15hybrid_step_fwd6Params.kd
    .uniform_work_group_size: 1
    .uses_dynamic_stack: false
    .vgpr_count:     256
    .vgpr_spill_count: 0
    .wavefront_size: 64
